# v55 + softmax loop VALU trims: threshold compare folded (thr+bias register), row-sum accumulator renamed (drops copy and zero-add), l update via v_fma (drops v_mov); -4 VALU per key tile
# speedup vs baseline: 1.0038x; 1.0016x over previous
.LBB0_913:
	s_xor_b64 s[0:1], s[2:3], -1
	v_writelane_b32 v244, s0, 9
	v_mov_b32_e32 v2, v0
	v_readlane_b32 s6, v245, 14
	v_writelane_b32 v244, s1, 10
	s_and_b64 s[0:1], s[2:3], exec
	v_readlane_b32 s0, v244, 3
	v_readlane_b32 s1, v244, 4
	s_cselect_b32 s0, s1, s0
	v_readlane_b32 s2, v244, 5
	s_lshl_b32 s9, s0, 8
	s_lshl_b32 s1, s0, 2
	s_lshl_b32 s2, s2, 1
	s_lshl_b32 s0, s0, 16
	s_or_b32 s2, s0, s2
	v_mov_b32_e32 v12, v0
	v_readlane_b32 s7, v245, 15
	s_add_u32 s6, s6, s2
	s_addc_u32 s7, s7, 0
	v_readfirstlane_b32 s2, v12
	s_ashr_i32 s3, s2, 6
	s_and_b32 s2, s2, 0x3fffffc0
	s_lshl_b32 s2, s2, 2
	v_and_b32_e32 v13, 31, v12
	s_add_i32 s95, s2, 0
	s_lshl_b32 s2, s3, 5
	v_or_b32_e32 v4, s2, v13
	v_ashrrev_i32_e32 v5, 31, v4
	v_bfe_u32 v14, v12, 5, 1
	v_lshlrev_b64 v[4:5], 8, v[4:5]
	v_lshl_add_u64 v[4:5], s[6:7], 0, v[4:5]
	v_lshlrev_b32_e32 v2, 4, v14
	v_lshl_add_u64 v[4:5], v[4:5], 0, v[2:3]
	global_load_dwordx4 v[100:103], v[4:5], off offset:128
	global_load_dwordx4 v[104:107], v[4:5], off offset:160
	global_load_dwordx4 v[108:111], v[4:5], off offset:192
	global_load_dwordx4 v[112:115], v[4:5], off offset:224
	v_ashrrev_i32_e32 v5, 4, v12
	v_lshlrev_b32_e32 v6, 1, v5
	v_lshrrev_b32_e32 v7, 1, v5
	v_and_b32_e32 v4, 0x1fffff3, v5
	v_and_b32_e32 v6, 8, v6
	v_and_b32_e32 v7, 4, v7
	v_or3_b32 v4, v4, v6, v7
	v_and_b32_e32 v6, 15, v12
	v_bitop3_b32 v6, v5, v6, 7 bitop3:0x6c
	v_lshlrev_b32_e32 v6, 3, v6
	v_lshl_or_b32 v4, v4, 7, v6
	v_bfe_u32 v6, v12, 2, 2
	v_and_or_b32 v5, v5, s90, v6
	v_lshrrev_b32_e32 v6, 1, v12
	s_or_b32 s92, s1, 3
	s_add_i32 s95, s95, 0x20400
	v_and_b32_e32 v6, 8, v6
	s_lshl_b32 s3, s3, 10
	s_add_i32 s86, s2, s9
	s_lshl_b32 s1, s92, 14
	v_or3_b32 v5, v5, v6, v7
	v_lshlrev_b32_e32 v15, 3, v12
	s_add_u32 s80, s74, s1
	v_lshlrev_b32_e32 v5, 7, v5
	v_and_b32_e32 v6, 0x60, v12
	v_and_b32_e32 v7, 24, v15
	s_addc_u32 s81, s75, 0
	v_or3_b32 v6, v5, v6, v7
	v_ashrrev_i32_e32 v5, 31, v4
	s_add_u32 s96, s76, s1
	v_lshlrev_b64 v[4:5], 1, v[4:5]
	s_addc_u32 s97, s77, 0
	s_add_i32 s8, s3, 0
	v_lshl_add_u64 v[8:9], s[80:81], 0, v[4:5]
	v_ashrrev_i32_e32 v7, 31, v6
	s_add_i32 m0, s8, 0x1c000
	v_lshlrev_b64 v[6:7], 1, v[6:7]
	global_load_lds_dwordx4 v[8:9], off
	v_lshl_add_u64 v[8:9], v[8:9], 0, s[84:85]
	s_add_i32 m0, s8, 0x1e000
	v_lshl_add_u64 v[10:11], s[96:97], 0, v[6:7]
	global_load_lds_dwordx4 v[8:9], off
	s_add_i32 m0, s8, 0xc000
	s_or_b32 s1, s0, 0x8000
	global_load_lds_dwordx4 v[10:11], off
	s_add_i32 m0, s8, 0xe000
	s_add_u32 s82, s74, s1
	s_addc_u32 s83, s75, 0
	v_lshl_add_u64 v[8:9], v[10:11], 0, s[84:85]
	s_add_u32 s88, s76, s1
	global_load_lds_dwordx4 v[8:9], off
	v_lshl_add_u64 v[8:9], s[82:83], 0, v[4:5]
	s_addc_u32 s89, s77, 0
	s_add_i32 m0, s8, 0x18000
	v_lshl_add_u64 v[10:11], s[88:89], 0, v[6:7]
	global_load_lds_dwordx4 v[8:9], off
	v_lshl_add_u64 v[8:9], v[8:9], 0, s[84:85]
	s_add_i32 m0, s8, 0x1a000
	v_lshl_add_u64 v[148:149], s[74:75], 0, v[4:5]
	global_load_lds_dwordx4 v[8:9], off
	s_add_i32 m0, s8, 0x8000
	v_lshl_add_u64 v[8:9], v[10:11], 0, s[84:85]
	global_load_lds_dwordx4 v[10:11], off
	s_add_i32 m0, s8, 0xa000
	v_lshlrev_b32_e32 v5, 4, v12
	global_load_lds_dwordx4 v[8:9], off
	v_lshl_add_u64 v[150:151], s[76:77], 0, v[6:7]
	v_lshlrev_b32_e32 v4, 1, v12
	v_and_b32_e32 v6, 0xc0, v5
	v_and_b32_e32 v5, 0x70, v5
	s_movk_i32 s3, 0x80
	v_and_b32_e32 v4, 32, v4
	v_bitop3_b32 v153, v2, v5, s3 bitop3:0x36
	s_movk_i32 s3, 0xa0
	v_and_or_b32 v4, v15, s93, v4
	v_bitop3_b32 v155, v2, v5, s3 bitop3:0x36
	s_movk_i32 s3, 0xc0
	s_addk_i32 s2, 0xff40
	v_and_b32_e32 v8, 63, v12
	v_lshlrev_b32_e32 v9, 3, v14
	s_waitcnt vmcnt(0)
	v_bitop3_b32 v156, v2, v5, s3 bitop3:0x36
	s_movk_i32 s3, 0xe0
	v_add3_u32 v158, v6, 0, v4
	v_or_b32_e32 v4, s2, v13
	v_mov_b32_e32 v18, v3
	v_mov_b32_e32 v19, v3
	v_lshlrev_b32_e32 v152, 8, v13
	v_bitop3_b32 v157, v2, v5, s3 bitop3:0x36
	v_cmp_gt_u32_e64 s[10:11], 32, v8
	v_lshl_add_u32 v154, v13, 2, s95
	v_sub_u32_e32 v159, v4, v9
	v_mov_b32_e32 v4, v3
	v_mov_b32_e32 v5, v3
	v_mov_b32_e32 v6, v3
	v_mov_b32_e32 v7, v3
	v_mov_b32_e32 v8, v3
	v_mov_b32_e32 v9, v3
	v_mov_b32_e32 v10, v3
	v_mov_b32_e32 v11, v3
	v_mov_b32_e32 v12, v3
	v_mov_b32_e32 v13, v3
	v_mov_b32_e32 v14, v3
	v_mov_b32_e32 v15, v3
	v_mov_b32_e32 v16, v3
	v_mov_b32_e32 v17, v3
	v_mov_b64_e32 v[34:35], v[18:19]
	v_mov_b64_e32 v[50:51], v[18:19]
	v_mov_b64_e32 v[66:67], v[18:19]
	s_add_i32 s1, s8, 0x10000
	s_or_b32 s90, s86, 31
	v_mov_b32_e32 v161, 0
	v_mov_b32_e32 v160, 0xf149f2ca
	v_mov_b32_e32 v240, 0xf149f2ca
	v_add_f32_e32 v239, s91, v240
	v_mov_b64_e32 v[184:185], 0
	v_mov_b64_e32 v[186:187], 0
	v_mov_b64_e32 v[188:189], 0
	v_mov_b64_e32 v[190:191], 0
	v_mov_b64_e32 v[192:193], 0
	v_mov_b64_e32 v[194:195], 0
	v_mov_b64_e32 v[196:197], 0
	v_mov_b64_e32 v[198:199], 0
	s_mov_b32 s2, s9
	s_mov_b32 s33, s0
	v_mov_b64_e32 v[32:33], v[16:17]
	v_mov_b64_e32 v[30:31], v[14:15]
	v_mov_b64_e32 v[28:29], v[12:13]
	v_mov_b64_e32 v[26:27], v[10:11]
	v_mov_b64_e32 v[24:25], v[8:9]
	v_mov_b64_e32 v[22:23], v[6:7]
	v_mov_b64_e32 v[20:21], v[4:5]
	v_mov_b64_e32 v[48:49], v[16:17]
	v_mov_b64_e32 v[46:47], v[14:15]
	v_mov_b64_e32 v[44:45], v[12:13]
	v_mov_b64_e32 v[42:43], v[10:11]
	v_mov_b64_e32 v[40:41], v[8:9]
	v_mov_b64_e32 v[38:39], v[6:7]
	v_mov_b64_e32 v[36:37], v[4:5]
	v_mov_b64_e32 v[64:65], v[16:17]
	v_mov_b64_e32 v[62:63], v[14:15]
	v_mov_b64_e32 v[60:61], v[12:13]
	v_mov_b64_e32 v[58:59], v[10:11]
	v_mov_b64_e32 v[56:57], v[8:9]
	v_mov_b64_e32 v[54:55], v[6:7]
	v_mov_b64_e32 v[52:53], v[4:5]
	s_mov_b32 s94, s92
	s_waitcnt vmcnt(0) lgkmcnt(0)
	s_barrier
	s_branch .LBB0_917

.LBB0_915:
	v_cvt_pk_bf16_f32 v166, v164, v85
	v_cvt_pk_bf16_f32 v167, v86, v87
	v_cvt_pk_bf16_f32 v168, v88, v89
	v_cvt_pk_bf16_f32 v169, v90, v165
	v_cvt_pk_bf16_f32 v86, v91, v92
	v_cvt_pk_bf16_f32 v87, v93, v94
	v_cvt_pk_bf16_f32 v88, v95, v96
	v_cvt_pk_bf16_f32 v89, v97, v98
	v_cvt_pk_bf16_f32 v68, v68, v69
	v_cvt_pk_bf16_f32 v69, v70, v71
	v_cvt_pk_bf16_f32 v70, v72, v73
	v_cvt_pk_bf16_f32 v71, v74, v84
	v_cvt_pk_bf16_f32 v72, v75, v76
	v_cvt_pk_bf16_f32 v73, v77, v78
	v_cvt_pk_bf16_f32 v74, v79, v80
	v_cvt_pk_bf16_f32 v75, v81, v82
	s_waitcnt lgkmcnt(0)
	v_add_f32_e32 v99, v241, v99
	v_fma_f32 v161, v161, v163, v99
	v_mfma_f32_32x32x16_bf16 v[52:67], v[166:169], v[144:147], v[52:67]
	v_mfma_f32_32x32x16_bf16 v[52:67], v[86:89], v[140:143], v[52:67]
	v_mfma_f32_32x32x16_bf16 v[52:67], v[68:71], v[136:139], v[52:67]
	v_mfma_f32_32x32x16_bf16 v[52:67], v[72:75], v[132:135], v[52:67]
	ds_read_b64_tr_b16 v[76:77], v162 offset:0x400
	ds_read_b64_tr_b16 v[78:79], v162 offset:0xc00
	ds_read_b64_tr_b16 v[80:81], v162 offset:0x1400
	ds_read_b64_tr_b16 v[82:83], v162 offset:0x1c00
	ds_read_b64_tr_b16 v[90:91], v162 offset:0x2400
	ds_read_b64_tr_b16 v[92:93], v162 offset:0x2c00
	ds_read_b64_tr_b16 v[94:95], v162 offset:0x3400
	ds_read_b64_tr_b16 v[96:97], v162 offset:0x3c00
	v_mfma_f32_32x32x16_bf16 v[36:51], v[166:169], v[128:131], v[36:51]
	v_mfma_f32_32x32x16_bf16 v[36:51], v[86:89], v[124:127], v[36:51]
	v_mfma_f32_32x32x16_bf16 v[36:51], v[68:71], v[120:123], v[36:51]
	v_mfma_f32_32x32x16_bf16 v[36:51], v[72:75], v[116:119], v[36:51]
	ds_read_b64_tr_b16 v[116:117], v162 offset:0x600
	ds_read_b64_tr_b16 v[118:119], v162 offset:0xe00
	ds_read_b64_tr_b16 v[120:121], v162 offset:0x1600
	ds_read_b64_tr_b16 v[122:123], v162 offset:0x1e00
	ds_read_b64_tr_b16 v[124:125], v162 offset:0x2600
	ds_read_b64_tr_b16 v[126:127], v162 offset:0x2e00
	ds_read_b64_tr_b16 v[128:129], v162 offset:0x3600
	ds_read_b64_tr_b16 v[130:131], v162 offset:0x3e00
	s_waitcnt lgkmcnt(8)
	v_mfma_f32_32x32x16_bf16 v[20:35], v[166:169], v[76:79], v[20:35]
	v_mfma_f32_32x32x16_bf16 v[20:35], v[86:89], v[80:83], v[20:35]
	v_mfma_f32_32x32x16_bf16 v[20:35], v[68:71], v[90:93], v[20:35]
	v_mfma_f32_32x32x16_bf16 v[20:35], v[72:75], v[94:97], v[20:35]
	s_waitcnt lgkmcnt(0)
	v_mfma_f32_32x32x16_bf16 v[4:19], v[166:169], v[116:119], v[4:19]
	v_mfma_f32_32x32x16_bf16 v[4:19], v[86:89], v[120:123], v[4:19]
	v_mfma_f32_32x32x16_bf16 v[4:19], v[68:71], v[124:127], v[4:19]
	v_mfma_f32_32x32x16_bf16 v[4:19], v[72:75], v[128:131], v[4:19]

.LBB0_923:
	s_nop 8
	v_max_f32_e32 v163, v84, v85
	v_max3_f32 v163, v163, v86, v87
	v_max3_f32 v163, v163, v88, v89
	v_max3_f32 v163, v163, v90, v91
	v_max3_f32 v163, v163, v92, v93
	v_max3_f32 v163, v163, v94, v95
	v_max3_f32 v163, v163, v96, v97
	v_max3_f32 v163, v163, v98, v99
	v_max3_f32 v163, v163, v68, v69
	v_max3_f32 v163, v163, v70, v71
	v_max3_f32 v163, v163, v72, v73
	v_max3_f32 v163, v163, v74, v75
	v_max3_f32 v163, v163, v76, v77
	v_max3_f32 v163, v163, v78, v79
	v_max3_f32 v163, v163, v80, v81
	v_max3_f32 v163, v163, v82, v83
	v_mov_b32_e32 v164, v163
	s_nop 1
	v_permlane32_swap_b32_e32 v163, v164
	v_max_f32_e32 v164, v163, v164
	v_cmp_ge_f32_e32 vcc, v239, v164
	s_cmp_eq_u64 vcc, exec
	v_mov_b32_e32 v163, 1.0
	s_cbranch_scc0 .LBB0_935
.LBB0_924:
	v_exp_f32_e32 v164, v84
	v_exp_f32_e32 v85, v85
	v_exp_f32_e32 v86, v86
	v_exp_f32_e32 v87, v87
	v_exp_f32_e32 v88, v88
	v_exp_f32_e32 v89, v89
	v_exp_f32_e32 v90, v90
	v_exp_f32_e32 v165, v91
	v_exp_f32_e32 v84, v75
	v_exp_f32_e32 v91, v92
	v_exp_f32_e32 v92, v93
	v_exp_f32_e32 v93, v94
	v_exp_f32_e32 v94, v95
	v_exp_f32_e32 v95, v96
	v_exp_f32_e32 v96, v97
	v_exp_f32_e32 v97, v98
	v_exp_f32_e32 v98, v99
	v_add_f32_e32 v241, v85, v164
	v_add_f32_e32 v241, v86, v241
	v_add_f32_e32 v241, v87, v241
	v_add_f32_e32 v241, v88, v241
	v_add_f32_e32 v241, v89, v241
	v_add_f32_e32 v241, v90, v241
	v_add_f32_e32 v241, v165, v241
	v_add_f32_e32 v241, v91, v241
	v_add_f32_e32 v241, v92, v241
	v_add_f32_e32 v241, v93, v241
	v_add_f32_e32 v241, v94, v241
	v_exp_f32_e32 v68, v68
	v_add_f32_e32 v241, v95, v241
	v_exp_f32_e32 v69, v69
	v_add_f32_e32 v241, v96, v241
	v_exp_f32_e32 v70, v70
	v_add_f32_e32 v241, v97, v241
	v_exp_f32_e32 v71, v71
	v_add_f32_e32 v241, v98, v241
	v_exp_f32_e32 v72, v72
	v_add_f32_e32 v241, v68, v241
	v_exp_f32_e32 v73, v73
	v_add_f32_e32 v241, v69, v241
	v_exp_f32_e32 v74, v74
	v_add_f32_e32 v241, v70, v241
	v_add_f32_e32 v241, v71, v241
	v_exp_f32_e32 v75, v76
	v_add_f32_e32 v241, v72, v241
	v_exp_f32_e32 v76, v77
	v_add_f32_e32 v241, v73, v241
	v_exp_f32_e32 v77, v78
	v_add_f32_e32 v241, v74, v241
	v_exp_f32_e32 v78, v79
	v_add_f32_e32 v241, v84, v241
	v_exp_f32_e32 v79, v80
	v_add_f32_e32 v241, v75, v241
	v_exp_f32_e32 v80, v81
	v_add_f32_e32 v241, v76, v241
	v_exp_f32_e32 v81, v82
	v_add_f32_e32 v241, v77, v241
	v_exp_f32_e32 v82, v83
	v_add_f32_e32 v241, v78, v241
	v_add_f32_e32 v241, v79, v241
	v_add_f32_e32 v241, v80, v241
	v_add_f32_e32 v241, v81, v241
	v_add_f32_e32 v241, v82, v241
	v_mov_b32_e32 v99, v241
	s_nop 1
	v_permlane32_swap_b32_e32 v241, v99
	v_cmp_gt_f32_e32 vcc, 1.0, v163
	s_cbranch_vccz .LBB0_928
	s_and_saveexec_b64 s[12:13], s[10:11]
	ds_write_b32 v154, v163 offset:128
	s_or_b64 exec, exec, s[12:13]
	s_waitcnt lgkmcnt(0)
	v_add_u32_e32 v178, s95, v2
	ds_read_b128 v[166:169], v178 offset:224
	ds_read_b128 v[170:173], v178 offset:192
	ds_read_b128 v[174:177], v178 offset:160
	ds_read_b128 v[178:181], v178 offset:128
	s_waitcnt lgkmcnt(0)
	s_waitcnt lgkmcnt(0)
	v_pk_mul_f32 v[64:65], v[166:167], v[64:65]
	v_pk_mul_f32 v[60:61], v[170:171], v[60:61]
	v_pk_mul_f32 v[56:57], v[174:175], v[56:57]
	v_pk_mul_f32 v[66:67], v[168:169], v[66:67]
	v_pk_mul_f32 v[62:63], v[172:173], v[62:63]
	v_pk_mul_f32 v[58:59], v[176:177], v[58:59]
	v_pk_mul_f32 v[54:55], v[180:181], v[54:55]
	v_pk_mul_f32 v[52:53], v[178:179], v[52:53]
	v_pk_mul_f32 v[48:49], v[166:167], v[48:49]
	v_pk_mul_f32 v[44:45], v[170:171], v[44:45]
	v_pk_mul_f32 v[40:41], v[174:175], v[40:41]
	v_pk_mul_f32 v[50:51], v[168:169], v[50:51]
	v_pk_mul_f32 v[46:47], v[172:173], v[46:47]
	v_pk_mul_f32 v[42:43], v[176:177], v[42:43]
	v_pk_mul_f32 v[38:39], v[180:181], v[38:39]
	v_pk_mul_f32 v[36:37], v[178:179], v[36:37]
	v_pk_mul_f32 v[32:33], v[166:167], v[32:33]
	v_pk_mul_f32 v[28:29], v[170:171], v[28:29]
	v_pk_mul_f32 v[24:25], v[174:175], v[24:25]
	v_pk_mul_f32 v[34:35], v[168:169], v[34:35]
	v_pk_mul_f32 v[30:31], v[172:173], v[30:31]
	v_pk_mul_f32 v[26:27], v[176:177], v[26:27]
	v_pk_mul_f32 v[22:23], v[180:181], v[22:23]
	v_pk_mul_f32 v[20:21], v[178:179], v[20:21]
	v_pk_mul_f32 v[16:17], v[166:167], v[16:17]
	v_pk_mul_f32 v[12:13], v[170:171], v[12:13]
	v_pk_mul_f32 v[8:9], v[174:175], v[8:9]
	v_pk_mul_f32 v[18:19], v[168:169], v[18:19]
	v_pk_mul_f32 v[14:15], v[172:173], v[14:15]
	v_pk_mul_f32 v[10:11], v[176:177], v[10:11]
	v_pk_mul_f32 v[6:7], v[180:181], v[6:7]
	v_pk_mul_f32 v[4:5], v[178:179], v[4:5]
.LBB0_928:
	v_cvt_pk_bf16_f32 v166, v164, v85
	v_cvt_pk_bf16_f32 v167, v86, v87
	v_cvt_pk_bf16_f32 v168, v88, v89
	v_cvt_pk_bf16_f32 v169, v90, v165
	v_cvt_pk_bf16_f32 v86, v91, v92
	v_cvt_pk_bf16_f32 v87, v93, v94
	v_cvt_pk_bf16_f32 v88, v95, v96
	v_cvt_pk_bf16_f32 v89, v97, v98
	v_cvt_pk_bf16_f32 v68, v68, v69
	v_cvt_pk_bf16_f32 v69, v70, v71
	v_cvt_pk_bf16_f32 v70, v72, v73
	v_cvt_pk_bf16_f32 v71, v74, v84
	v_cvt_pk_bf16_f32 v72, v75, v76
	v_cvt_pk_bf16_f32 v73, v77, v78
	v_cvt_pk_bf16_f32 v74, v79, v80
	v_cvt_pk_bf16_f32 v75, v81, v82
	s_waitcnt lgkmcnt(0)
	v_add_f32_e32 v99, v241, v99
	v_fma_f32 v161, v161, v163, v99
	v_mfma_f32_32x32x16_bf16 v[52:67], v[166:169], v[144:147], v[52:67]
	v_mfma_f32_32x32x16_bf16 v[52:67], v[86:89], v[140:143], v[52:67]
	v_mfma_f32_32x32x16_bf16 v[52:67], v[68:71], v[136:139], v[52:67]
	v_mfma_f32_32x32x16_bf16 v[52:67], v[72:75], v[132:135], v[52:67]
	ds_read_b64_tr_b16 v[76:77], v162 offset:0x400
	ds_read_b64_tr_b16 v[78:79], v162 offset:0xc00
	ds_read_b64_tr_b16 v[80:81], v162 offset:0x1400
	ds_read_b64_tr_b16 v[82:83], v162 offset:0x1c00
	ds_read_b64_tr_b16 v[90:91], v162 offset:0x2400
	ds_read_b64_tr_b16 v[92:93], v162 offset:0x2c00
	ds_read_b64_tr_b16 v[94:95], v162 offset:0x3400
	ds_read_b64_tr_b16 v[96:97], v162 offset:0x3c00
	v_mfma_f32_32x32x16_bf16 v[36:51], v[166:169], v[128:131], v[36:51]
	v_mfma_f32_32x32x16_bf16 v[36:51], v[86:89], v[124:127], v[36:51]
	v_mfma_f32_32x32x16_bf16 v[36:51], v[68:71], v[120:123], v[36:51]
	v_mfma_f32_32x32x16_bf16 v[36:51], v[72:75], v[116:119], v[36:51]
	ds_read_b64_tr_b16 v[116:117], v162 offset:0x600
	ds_read_b64_tr_b16 v[118:119], v162 offset:0xe00
	ds_read_b64_tr_b16 v[120:121], v162 offset:0x1600
	ds_read_b64_tr_b16 v[122:123], v162 offset:0x1e00
	ds_read_b64_tr_b16 v[124:125], v162 offset:0x2600
	ds_read_b64_tr_b16 v[126:127], v162 offset:0x2e00
	ds_read_b64_tr_b16 v[128:129], v162 offset:0x3600
	ds_read_b64_tr_b16 v[130:131], v162 offset:0x3e00
	s_waitcnt lgkmcnt(8)
	v_mfma_f32_32x32x16_bf16 v[20:35], v[166:169], v[76:79], v[20:35]
	v_mfma_f32_32x32x16_bf16 v[20:35], v[86:89], v[80:83], v[20:35]
	v_mfma_f32_32x32x16_bf16 v[20:35], v[68:71], v[90:93], v[20:35]
	v_mfma_f32_32x32x16_bf16 v[20:35], v[72:75], v[94:97], v[20:35]
	s_waitcnt lgkmcnt(0)
	v_mfma_f32_32x32x16_bf16 v[4:19], v[166:169], v[116:119], v[4:19]
	v_mfma_f32_32x32x16_bf16 v[4:19], v[86:89], v[120:123], v[4:19]
	v_mfma_f32_32x32x16_bf16 v[4:19], v[68:71], v[124:127], v[4:19]
	v_mfma_f32_32x32x16_bf16 v[4:19], v[72:75], v[128:131], v[4:19]
	s_add_i32 s3, s2, 0x80
	s_cmp_gt_i32 s3, s90
	s_cbranch_scc1 .LBB0_916

.LBB0_932:
	v_exp_f32_e32 v164, v84
	v_exp_f32_e32 v85, v85
	v_exp_f32_e32 v86, v86
	v_exp_f32_e32 v87, v87
	v_exp_f32_e32 v88, v88
	v_exp_f32_e32 v89, v89
	v_exp_f32_e32 v90, v90
	v_exp_f32_e32 v165, v91
	v_exp_f32_e32 v84, v75
	v_exp_f32_e32 v91, v92
	v_exp_f32_e32 v92, v93
	v_exp_f32_e32 v93, v94
	v_exp_f32_e32 v94, v95
	v_exp_f32_e32 v95, v96
	v_exp_f32_e32 v96, v97
	v_exp_f32_e32 v97, v98
	v_exp_f32_e32 v98, v99
	v_add_f32_e32 v241, v85, v164
	v_add_f32_e32 v241, v86, v241
	v_add_f32_e32 v241, v87, v241
	v_add_f32_e32 v241, v88, v241
	v_add_f32_e32 v241, v89, v241
	v_add_f32_e32 v241, v90, v241
	v_add_f32_e32 v241, v165, v241
	v_add_f32_e32 v241, v91, v241
	v_add_f32_e32 v241, v92, v241
	v_add_f32_e32 v241, v93, v241
	v_add_f32_e32 v241, v94, v241
	v_exp_f32_e32 v68, v68
	v_add_f32_e32 v241, v95, v241
	v_exp_f32_e32 v69, v69
	v_add_f32_e32 v241, v96, v241
	v_exp_f32_e32 v70, v70
	v_add_f32_e32 v241, v97, v241
	v_exp_f32_e32 v71, v71
	v_add_f32_e32 v241, v98, v241
	v_exp_f32_e32 v72, v72
	v_add_f32_e32 v241, v68, v241
	v_exp_f32_e32 v73, v73
	v_add_f32_e32 v241, v69, v241
	v_exp_f32_e32 v74, v74
	v_add_f32_e32 v241, v70, v241
	v_add_f32_e32 v241, v71, v241
	v_exp_f32_e32 v75, v76
	v_add_f32_e32 v241, v72, v241
	v_exp_f32_e32 v76, v77
	v_add_f32_e32 v241, v73, v241
	v_exp_f32_e32 v77, v78
	v_add_f32_e32 v241, v74, v241
	v_exp_f32_e32 v78, v79
	v_add_f32_e32 v241, v84, v241
	v_exp_f32_e32 v79, v80
	v_add_f32_e32 v241, v75, v241
	v_exp_f32_e32 v80, v81
	v_add_f32_e32 v241, v76, v241
	v_exp_f32_e32 v81, v82
	v_add_f32_e32 v241, v77, v241
	v_exp_f32_e32 v82, v83
	v_add_f32_e32 v241, v78, v241
	v_add_f32_e32 v241, v79, v241
	v_add_f32_e32 v241, v80, v241
	v_add_f32_e32 v241, v81, v241
	v_add_f32_e32 v241, v82, v241
	v_mov_b32_e32 v99, v241
	s_nop 1
	v_permlane32_swap_b32_e32 v241, v99
	v_cmp_gt_f32_e32 vcc, 1.0, v163
	s_cbranch_vccz .LBB0_915
	s_and_saveexec_b64 s[12:13], s[10:11]
	s_cbranch_execz .LBB0_914
	ds_write_b32 v154, v163 offset:128
	s_branch .LBB0_914
.LBB0_935:
	v_sub_f32_e32 v241, v164, v184
	v_max_f32_e32 v241, v160, v241
	v_sub_f32_e32 v163, v160, v241
	v_exp_f32_e32 v163, v163
	v_add_f32_e32 v242, v241, v184
	v_mov_b32_e32 v160, v241
	v_sub_f32_e32 v84, v84, v242
	v_sub_f32_e32 v85, v85, v242
	v_sub_f32_e32 v86, v86, v242
	v_sub_f32_e32 v87, v87, v242
	v_sub_f32_e32 v88, v88, v242
	v_sub_f32_e32 v89, v89, v242
	v_sub_f32_e32 v90, v90, v242
	v_sub_f32_e32 v91, v91, v242
	v_sub_f32_e32 v92, v92, v242
	v_sub_f32_e32 v93, v93, v242
	v_sub_f32_e32 v94, v94, v242
	v_sub_f32_e32 v95, v95, v242
	v_sub_f32_e32 v96, v96, v242
	v_sub_f32_e32 v97, v97, v242
	v_sub_f32_e32 v98, v98, v242
	v_sub_f32_e32 v99, v99, v242
	v_sub_f32_e32 v68, v68, v242
	v_sub_f32_e32 v69, v69, v242
	v_sub_f32_e32 v70, v70, v242
	v_sub_f32_e32 v71, v71, v242
	v_sub_f32_e32 v72, v72, v242
	v_sub_f32_e32 v73, v73, v242
	v_sub_f32_e32 v74, v74, v242
	v_sub_f32_e32 v75, v75, v242
	v_sub_f32_e32 v76, v76, v242
	v_sub_f32_e32 v77, v77, v242
	v_sub_f32_e32 v78, v78, v242
	v_sub_f32_e32 v79, v79, v242
	v_sub_f32_e32 v80, v80, v242
	v_sub_f32_e32 v81, v81, v242
	v_sub_f32_e32 v82, v82, v242
	v_sub_f32_e32 v83, v83, v242
	v_cmp_lt_f32_e32 vcc, 0xf0000000, v241
	v_sub_f32_e32 v242, 0, v241
	s_nop 0
	v_cndmask_b32_e32 v242, 0, v242, vcc
	v_add_f32_e32 v240, v241, v242
	v_add_f32_e32 v239, s91, v240
	v_mov_b32_e32 v184, v242
	v_mov_b32_e32 v185, v242
	v_mov_b32_e32 v186, v242
	v_mov_b32_e32 v187, v242
	v_mov_b32_e32 v188, v242
	v_mov_b32_e32 v189, v242
	v_mov_b32_e32 v190, v242
	v_mov_b32_e32 v191, v242
	v_mov_b32_e32 v192, v242
	v_mov_b32_e32 v193, v242
	v_mov_b32_e32 v194, v242
	v_mov_b32_e32 v195, v242
	v_mov_b32_e32 v196, v242
	v_mov_b32_e32 v197, v242
	v_mov_b32_e32 v198, v242
	v_mov_b32_e32 v199, v242
	s_branch .LBB0_924
.LBB0_936:
	v_sub_f32_e32 v241, v164, v184
	v_max_f32_e32 v241, v160, v241
	v_sub_f32_e32 v163, v160, v241
	v_exp_f32_e32 v163, v163
	v_add_f32_e32 v242, v241, v184
	v_mov_b32_e32 v160, v241
	v_sub_f32_e32 v84, v84, v242
	v_sub_f32_e32 v85, v85, v242
	v_sub_f32_e32 v86, v86, v242
	v_sub_f32_e32 v87, v87, v242
	v_sub_f32_e32 v88, v88, v242
	v_sub_f32_e32 v89, v89, v242
	v_sub_f32_e32 v90, v90, v242
	v_sub_f32_e32 v91, v91, v242
	v_sub_f32_e32 v92, v92, v242
	v_sub_f32_e32 v93, v93, v242
	v_sub_f32_e32 v94, v94, v242
	v_sub_f32_e32 v95, v95, v242
	v_sub_f32_e32 v96, v96, v242
	v_sub_f32_e32 v97, v97, v242
	v_sub_f32_e32 v98, v98, v242
	v_sub_f32_e32 v99, v99, v242
	v_sub_f32_e32 v68, v68, v242
	v_sub_f32_e32 v69, v69, v242
	v_sub_f32_e32 v70, v70, v242
	v_sub_f32_e32 v71, v71, v242
	v_sub_f32_e32 v72, v72, v242
	v_sub_f32_e32 v73, v73, v242
	v_sub_f32_e32 v74, v74, v242
	v_sub_f32_e32 v75, v75, v242
	v_sub_f32_e32 v76, v76, v242
	v_sub_f32_e32 v77, v77, v242
	v_sub_f32_e32 v78, v78, v242
	v_sub_f32_e32 v79, v79, v242
	v_sub_f32_e32 v80, v80, v242
	v_sub_f32_e32 v81, v81, v242
	v_sub_f32_e32 v82, v82, v242
	v_sub_f32_e32 v83, v83, v242
	v_cmp_lt_f32_e32 vcc, 0xf0000000, v241
	v_sub_f32_e32 v242, 0, v241
	s_nop 0
	v_cndmask_b32_e32 v242, 0, v242, vcc
	v_add_f32_e32 v240, v241, v242
	v_add_f32_e32 v239, s91, v240
	v_mov_b32_e32 v184, v242
	v_mov_b32_e32 v185, v242
	v_mov_b32_e32 v186, v242
	v_mov_b32_e32 v187, v242
	v_mov_b32_e32 v188, v242
	v_mov_b32_e32 v189, v242
	v_mov_b32_e32 v190, v242
	v_mov_b32_e32 v191, v242
	v_mov_b32_e32 v192, v242
	v_mov_b32_e32 v193, v242
	v_mov_b32_e32 v194, v242
	v_mov_b32_e32 v195, v242
	v_mov_b32_e32 v196, v242
	v_mov_b32_e32 v197, v242
	v_mov_b32_e32 v198, v242
	v_mov_b32_e32 v199, v242
	s_branch .LBB0_932
	s_nop 0
	s_nop 0
	s_nop 0
	s_nop 0
	s_nop 0
	s_nop 0
	s_nop 0
	s_nop 0
	s_nop 0
	s_nop 0
	s_nop 0
	s_nop 0
	s_nop 0
	s_nop 0
.LBB0_937:
	s_and_saveexec_b64 s[2:3], s[10:11]
	ds_write_b32 v154, v161
	s_or_b64 exec, exec, s[2:3]
	s_waitcnt lgkmcnt(0)
	v_add_u32_e32 v2, s95, v2
	ds_read_b128 v[68:71], v2
	ds_read_b128 v[72:75], v2 offset:32
	v_readlane_b32 s2, v245, 62
	v_readlane_b32 s3, v245, 63
	s_mov_b32 s90, 0x1fffff0
	s_waitcnt lgkmcnt(1)
	v_rcp_f32_e32 v68, v68
	v_rcp_f32_e32 v69, v69
	v_rcp_f32_e32 v70, v70
	v_rcp_f32_e32 v71, v71
	s_waitcnt lgkmcnt(0)
	v_rcp_f32_e32 v72, v72
	v_pk_mul_f32 v[52:53], v[68:69], v[52:53]
	v_pk_mul_f32 v[36:37], v[68:69], v[36:37]
	v_pk_mul_f32 v[20:21], v[68:69], v[20:21]
	v_pk_mul_f32 v[4:5], v[68:69], v[4:5]
	v_pk_mul_f32 v[54:55], v[70:71], v[54:55]
	v_rcp_f32_e32 v73, v73
	v_pk_mul_f32 v[38:39], v[70:71], v[38:39]
	v_pk_mul_f32 v[22:23], v[70:71], v[22:23]
	v_pk_mul_f32 v[6:7], v[70:71], v[6:7]
	ds_read_b128 v[68:71], v2 offset:64
	v_pk_mul_f32 v[56:57], v[72:73], v[56:57]
	v_pk_mul_f32 v[40:41], v[72:73], v[40:41]
	v_rcp_f32_e32 v76, v74
	v_rcp_f32_e32 v77, v75
	v_pk_mul_f32 v[24:25], v[72:73], v[24:25]
	v_pk_mul_f32 v[8:9], v[72:73], v[8:9]
	ds_read_b128 v[72:75], v2 offset:96
	s_waitcnt lgkmcnt(1)
	v_rcp_f32_e32 v68, v68
	v_rcp_f32_e32 v69, v69
	v_rcp_f32_e32 v70, v70
	v_rcp_f32_e32 v71, v71
	v_mov_b32_e32 v2, v0
	v_pk_mul_f32 v[60:61], v[68:69], v[60:61]
	v_pk_mul_f32 v[44:45], v[68:69], v[44:45]
	v_pk_mul_f32 v[28:29], v[68:69], v[28:29]
	v_pk_mul_f32 v[12:13], v[68:69], v[12:13]
	s_waitcnt lgkmcnt(0)
	v_rcp_f32_e32 v68, v72
	v_rcp_f32_e32 v69, v73
	v_pk_mul_f32 v[62:63], v[70:71], v[62:63]
	v_pk_mul_f32 v[46:47], v[70:71], v[46:47]
	v_pk_mul_f32 v[30:31], v[70:71], v[30:31]
	v_pk_mul_f32 v[14:15], v[70:71], v[14:15]
	v_rcp_f32_e32 v70, v74
	v_rcp_f32_e32 v71, v75
	v_pk_mul_f32 v[64:65], v[68:69], v[64:65]
	v_pk_mul_f32 v[48:49], v[68:69], v[48:49]
	v_pk_mul_f32 v[32:33], v[68:69], v[32:33]
	v_pk_mul_f32 v[16:17], v[68:69], v[16:17]
	s_waitcnt lgkmcnt(0)
	v_pk_mul_f32 v[58:59], v[76:77], v[58:59]
	v_lshlrev_b32_e32 v68, 6, v2
	v_ashrrev_i32_e32 v69, 31, v68
	v_lshl_add_u64 v[148:149], v[68:69], 2, s[2:3]
	v_pk_mul_f32 v[42:43], v[76:77], v[42:43]
	v_pk_mul_f32 v[26:27], v[76:77], v[26:27]
	v_pk_mul_f32 v[10:11], v[76:77], v[10:11]
	v_pk_mul_f32 v[66:67], v[70:71], v[66:67]
	v_pk_mul_f32 v[50:51], v[70:71], v[50:51]
	v_pk_mul_f32 v[34:35], v[70:71], v[34:35]
	v_pk_mul_f32 v[18:19], v[70:71], v[18:19]
	global_store_dwordx4 v[148:149], v[52:55], off
	global_store_dwordx4 v[148:149], v[56:59], off offset:16
	global_store_dwordx4 v[148:149], v[60:63], off offset:32
	global_store_dwordx4 v[148:149], v[64:67], off offset:48
	global_store_dwordx4 v[148:149], v[36:39], off offset:64
	global_store_dwordx4 v[148:149], v[40:43], off offset:80
	global_store_dwordx4 v[148:149], v[44:47], off offset:96
	global_store_dwordx4 v[148:149], v[48:51], off offset:112
	global_store_dwordx4 v[148:149], v[20:23], off offset:128
	global_store_dwordx4 v[148:149], v[24:27], off offset:144
	global_store_dwordx4 v[148:149], v[28:31], off offset:160
	global_store_dwordx4 v[148:149], v[32:35], off offset:176
	global_store_dwordx4 v[148:149], v[4:7], off offset:192
	global_store_dwordx4 v[148:149], v[8:11], off offset:208
	global_store_dwordx4 v[148:149], v[12:15], off offset:224
	global_store_dwordx4 v[148:149], v[16:19], off offset:240
	v_mov_b32_e32 v163, 0
	v_mov_b32_e32 v12, v0
	v_mov_b32_e32 v18, v3
	v_readfirstlane_b32 s1, v12
	s_ashr_i32 s2, s1, 6
	v_and_b32_e32 v13, 31, v12
	s_lshl_b32 s3, s2, 5
	v_or_b32_e32 v4, s3, v13
	v_ashrrev_i32_e32 v5, 31, v4
	v_bfe_u32 v14, v12, 5, 1
	v_lshlrev_b64 v[4:5], 8, v[4:5]
	v_lshl_add_u64 v[4:5], s[6:7], 0, v[4:5]
	v_lshlrev_b32_e32 v2, 4, v14
	v_lshl_add_u64 v[4:5], v[4:5], 0, v[2:3]
	global_load_dwordx4 v[100:103], v[4:5], off
	global_load_dwordx4 v[104:107], v[4:5], off offset:32
	global_load_dwordx4 v[108:111], v[4:5], off offset:64
	global_load_dwordx4 v[112:115], v[4:5], off offset:96
	v_ashrrev_i32_e32 v5, 4, v12
	v_lshlrev_b32_e32 v6, 1, v5
	v_lshrrev_b32_e32 v7, 1, v5
	v_and_b32_e32 v4, 0x1fffff3, v5
	v_and_b32_e32 v6, 8, v6
	v_and_b32_e32 v7, 4, v7
	v_or3_b32 v4, v4, v6, v7
	v_and_b32_e32 v6, 15, v12
	v_bitop3_b32 v6, v5, v6, 7 bitop3:0x6c
	v_lshlrev_b32_e32 v6, 3, v6
	v_lshl_or_b32 v4, v4, 7, v6
	v_bfe_u32 v6, v12, 2, 2
	v_and_or_b32 v5, v5, s90, v6
	v_lshrrev_b32_e32 v6, 1, v12
	v_and_b32_e32 v6, 8, v6
	v_or3_b32 v5, v5, v6, v7
	v_lshlrev_b32_e32 v15, 3, v12
	v_lshlrev_b32_e32 v5, 7, v5
	v_and_b32_e32 v6, 0x60, v12
	v_and_b32_e32 v7, 24, v15
	v_or3_b32 v6, v5, v6, v7
	s_lshl_b32 s2, s2, 10
	v_ashrrev_i32_e32 v5, 31, v4
	v_lshlrev_b64 v[4:5], 1, v[4:5]
	s_add_i32 s8, s2, 0
	v_lshl_add_u64 v[8:9], s[80:81], 0, v[4:5]
	v_ashrrev_i32_e32 v7, 31, v6
	s_add_i32 m0, s8, 0x1c000
	v_lshlrev_b64 v[6:7], 1, v[6:7]
	global_load_lds_dwordx4 v[8:9], off
	v_lshl_add_u64 v[8:9], v[8:9], 0, s[84:85]
	s_add_i32 m0, s8, 0x1e000
	v_lshl_add_u64 v[10:11], s[96:97], 0, v[6:7]
	global_load_lds_dwordx4 v[8:9], off
	s_add_i32 m0, s8, 0xc000
	v_lshl_add_u64 v[8:9], v[10:11], 0, s[84:85]
	global_load_lds_dwordx4 v[10:11], off
	s_add_i32 m0, s8, 0xe000
	v_lshl_add_u64 v[10:11], s[88:89], 0, v[6:7]
	global_load_lds_dwordx4 v[8:9], off
	v_lshl_add_u64 v[8:9], s[82:83], 0, v[4:5]
	s_add_i32 m0, s8, 0x18000
	s_and_b32 s1, s1, 0x3fffffc0
	global_load_lds_dwordx4 v[8:9], off
	v_lshl_add_u64 v[8:9], v[8:9], 0, s[84:85]
	s_add_i32 m0, s8, 0x1a000
	v_lshl_add_u64 v[150:151], s[74:75], 0, v[4:5]
	global_load_lds_dwordx4 v[8:9], off
	s_add_i32 m0, s8, 0x8000
	v_lshl_add_u64 v[8:9], v[10:11], 0, s[84:85]
	global_load_lds_dwordx4 v[10:11], off
	s_add_i32 m0, s8, 0xa000
	v_lshlrev_b32_e32 v4, 1, v12
	global_load_lds_dwordx4 v[8:9], off
	s_lshl_b32 s1, s1, 2
	v_and_b32_e32 v4, 32, v4
	v_lshlrev_b32_e32 v5, 4, v12
	s_add_i32 s78, s1, 0
	s_add_i32 s79, s3, s9
	v_lshl_add_u64 v[152:153], s[76:77], 0, v[6:7]
	v_and_b32_e32 v6, 0xc0, v5
	v_and_or_b32 v4, v15, s93, v4
	s_movk_i32 s2, 0x70
	s_addk_i32 s3, 0xff40
	s_add_i32 s78, s78, 0x20400
	v_and_b32_e32 v8, 63, v12
	v_lshlrev_b32_e32 v9, 3, v14
	s_waitcnt vmcnt(0)
	v_and_b32_e32 v7, 0x70, v5
	v_bitop3_b32 v156, v2, v5, s2 bitop3:0x78
	s_movk_i32 s2, 0x60
	v_add3_u32 v160, v6, 0, v4
	v_or_b32_e32 v4, s3, v13
	v_mov_b32_e32 v19, v3
	v_lshlrev_b32_e32 v154, 8, v13
	v_bitop3_b32 v157, v2, v7, 32 bitop3:0x36
	v_bitop3_b32 v158, v2, v7, 64 bitop3:0x36
	v_bitop3_b32 v159, v2, v7, s2 bitop3:0x36
	v_cmp_gt_u32_e64 s[10:11], 32, v8
	v_lshl_add_u32 v155, v13, 2, s78
	v_sub_u32_e32 v161, v4, v9
	v_mov_b32_e32 v4, v3
	v_mov_b32_e32 v5, v3
	v_mov_b32_e32 v6, v3
	v_mov_b32_e32 v7, v3
	v_mov_b32_e32 v8, v3
	v_mov_b32_e32 v9, v3
	v_mov_b32_e32 v10, v3
	v_mov_b32_e32 v11, v3
	v_mov_b32_e32 v12, v3
	v_mov_b32_e32 v13, v3
	v_mov_b32_e32 v14, v3
	v_mov_b32_e32 v15, v3
	v_mov_b32_e32 v16, v3
	v_mov_b32_e32 v17, v3
	v_mov_b64_e32 v[34:35], v[18:19]
	v_mov_b64_e32 v[50:51], v[18:19]
	v_mov_b64_e32 v[66:67], v[18:19]
	s_add_i32 s1, s8, 0x10000
	s_or_b32 s80, s79, 31
	v_mov_b32_e32 v162, 0xf149f2ca
	v_mov_b32_e32 v240, 0xf149f2ca
	v_add_f32_e32 v239, s91, v240
	v_mov_b64_e32 v[184:185], 0
	v_mov_b64_e32 v[186:187], 0
	v_mov_b64_e32 v[188:189], 0
	v_mov_b64_e32 v[190:191], 0
	v_mov_b64_e32 v[192:193], 0
	v_mov_b64_e32 v[194:195], 0
	v_mov_b64_e32 v[196:197], 0
	v_mov_b64_e32 v[198:199], 0
	s_mov_b32 s2, s9
	v_mov_b64_e32 v[32:33], v[16:17]
	v_mov_b64_e32 v[30:31], v[14:15]
	v_mov_b64_e32 v[28:29], v[12:13]
	v_mov_b64_e32 v[26:27], v[10:11]
	v_mov_b64_e32 v[24:25], v[8:9]
	v_mov_b64_e32 v[22:23], v[6:7]
	v_mov_b64_e32 v[20:21], v[4:5]
	v_mov_b64_e32 v[48:49], v[16:17]
	v_mov_b64_e32 v[46:47], v[14:15]
	v_mov_b64_e32 v[44:45], v[12:13]
	v_mov_b64_e32 v[42:43], v[10:11]
	v_mov_b64_e32 v[40:41], v[8:9]
	v_mov_b64_e32 v[38:39], v[6:7]
	v_mov_b64_e32 v[36:37], v[4:5]
	v_mov_b64_e32 v[64:65], v[16:17]
	v_mov_b64_e32 v[62:63], v[14:15]
	v_mov_b64_e32 v[60:61], v[12:13]
	v_mov_b64_e32 v[58:59], v[10:11]
	v_mov_b64_e32 v[56:57], v[8:9]
	v_mov_b64_e32 v[54:55], v[6:7]
	v_mov_b64_e32 v[52:53], v[4:5]
	s_waitcnt vmcnt(0) lgkmcnt(0)
	s_barrier
	s_branch .LBB0_943

.LBB0_941:
	v_cvt_pk_bf16_f32 v168, v166, v85
	v_cvt_pk_bf16_f32 v169, v86, v87
	v_cvt_pk_bf16_f32 v170, v88, v89
	v_cvt_pk_bf16_f32 v171, v90, v167
	v_cvt_pk_bf16_f32 v86, v91, v92
	v_cvt_pk_bf16_f32 v87, v93, v94
	v_cvt_pk_bf16_f32 v88, v95, v96
	v_cvt_pk_bf16_f32 v89, v97, v98
	v_cvt_pk_bf16_f32 v68, v68, v69
	v_cvt_pk_bf16_f32 v69, v70, v71
	v_cvt_pk_bf16_f32 v70, v72, v73
	v_cvt_pk_bf16_f32 v71, v74, v84
	v_cvt_pk_bf16_f32 v72, v75, v76
	v_cvt_pk_bf16_f32 v73, v77, v78
	v_cvt_pk_bf16_f32 v74, v79, v80
	v_cvt_pk_bf16_f32 v75, v81, v82
	s_waitcnt lgkmcnt(0)
	v_add_f32_e32 v99, v241, v99
	v_fma_f32 v163, v163, v165, v99
	v_mfma_f32_32x32x16_bf16 v[52:67], v[168:171], v[144:147], v[52:67]
	v_mfma_f32_32x32x16_bf16 v[52:67], v[86:89], v[140:143], v[52:67]
	v_mfma_f32_32x32x16_bf16 v[52:67], v[68:71], v[136:139], v[52:67]
	v_mfma_f32_32x32x16_bf16 v[52:67], v[72:75], v[132:135], v[52:67]
	ds_read_b64_tr_b16 v[76:77], v164 offset:0x400
	ds_read_b64_tr_b16 v[78:79], v164 offset:0xc00
	ds_read_b64_tr_b16 v[80:81], v164 offset:0x1400
	ds_read_b64_tr_b16 v[82:83], v164 offset:0x1c00
	ds_read_b64_tr_b16 v[90:91], v164 offset:0x2400
	ds_read_b64_tr_b16 v[92:93], v164 offset:0x2c00
	ds_read_b64_tr_b16 v[94:95], v164 offset:0x3400
	ds_read_b64_tr_b16 v[96:97], v164 offset:0x3c00
	v_mfma_f32_32x32x16_bf16 v[36:51], v[168:171], v[128:131], v[36:51]
	v_mfma_f32_32x32x16_bf16 v[36:51], v[86:89], v[124:127], v[36:51]
	v_mfma_f32_32x32x16_bf16 v[36:51], v[68:71], v[120:123], v[36:51]
	v_mfma_f32_32x32x16_bf16 v[36:51], v[72:75], v[116:119], v[36:51]
	ds_read_b64_tr_b16 v[116:117], v164 offset:0x600
	ds_read_b64_tr_b16 v[118:119], v164 offset:0xe00
	ds_read_b64_tr_b16 v[120:121], v164 offset:0x1600
	ds_read_b64_tr_b16 v[122:123], v164 offset:0x1e00
	ds_read_b64_tr_b16 v[124:125], v164 offset:0x2600
	ds_read_b64_tr_b16 v[126:127], v164 offset:0x2e00
	ds_read_b64_tr_b16 v[128:129], v164 offset:0x3600
	ds_read_b64_tr_b16 v[130:131], v164 offset:0x3e00
	s_waitcnt lgkmcnt(8)
	v_mfma_f32_32x32x16_bf16 v[20:35], v[168:171], v[76:79], v[20:35]
	v_mfma_f32_32x32x16_bf16 v[20:35], v[86:89], v[80:83], v[20:35]
	v_mfma_f32_32x32x16_bf16 v[20:35], v[68:71], v[90:93], v[20:35]
	v_mfma_f32_32x32x16_bf16 v[20:35], v[72:75], v[94:97], v[20:35]
	s_waitcnt lgkmcnt(0)
	v_mfma_f32_32x32x16_bf16 v[4:19], v[168:171], v[116:119], v[4:19]
	v_mfma_f32_32x32x16_bf16 v[4:19], v[86:89], v[120:123], v[4:19]
	v_mfma_f32_32x32x16_bf16 v[4:19], v[68:71], v[124:127], v[4:19]
	v_mfma_f32_32x32x16_bf16 v[4:19], v[72:75], v[128:131], v[4:19]

.LBB0_949:
	s_nop 8
	v_max_f32_e32 v165, v84, v85
	v_max3_f32 v165, v165, v86, v87
	v_max3_f32 v165, v165, v88, v89
	v_max3_f32 v165, v165, v90, v91
	v_max3_f32 v165, v165, v92, v93
	v_max3_f32 v165, v165, v94, v95
	v_max3_f32 v165, v165, v96, v97
	v_max3_f32 v165, v165, v98, v99
	v_max3_f32 v165, v165, v68, v69
	v_max3_f32 v165, v165, v70, v71
	v_max3_f32 v165, v165, v72, v73
	v_max3_f32 v165, v165, v74, v75
	v_max3_f32 v165, v165, v76, v77
	v_max3_f32 v165, v165, v78, v79
	v_max3_f32 v165, v165, v80, v81
	v_max3_f32 v165, v165, v82, v83
	v_mov_b32_e32 v166, v165
	s_nop 1
	v_permlane32_swap_b32_e32 v165, v166
	v_max_f32_e32 v166, v165, v166
	v_cmp_ge_f32_e32 vcc, v239, v166
	s_cmp_eq_u64 vcc, exec
	v_mov_b32_e32 v165, 1.0
	s_cbranch_scc0 .LBB0_961
.LBB0_950:
	v_exp_f32_e32 v166, v84
	v_exp_f32_e32 v85, v85
	v_exp_f32_e32 v86, v86
	v_exp_f32_e32 v87, v87
	v_exp_f32_e32 v88, v88
	v_exp_f32_e32 v89, v89
	v_exp_f32_e32 v90, v90
	v_exp_f32_e32 v167, v91
	v_exp_f32_e32 v84, v75
	v_exp_f32_e32 v91, v92
	v_exp_f32_e32 v92, v93
	v_exp_f32_e32 v93, v94
	v_exp_f32_e32 v94, v95
	v_exp_f32_e32 v95, v96
	v_exp_f32_e32 v96, v97
	v_exp_f32_e32 v97, v98
	v_exp_f32_e32 v98, v99
	v_add_f32_e32 v241, v85, v166
	v_add_f32_e32 v241, v86, v241
	v_add_f32_e32 v241, v87, v241
	v_add_f32_e32 v241, v88, v241
	v_add_f32_e32 v241, v89, v241
	v_add_f32_e32 v241, v90, v241
	v_add_f32_e32 v241, v167, v241
	v_add_f32_e32 v241, v91, v241
	v_add_f32_e32 v241, v92, v241
	v_add_f32_e32 v241, v93, v241
	v_add_f32_e32 v241, v94, v241
	v_exp_f32_e32 v68, v68
	v_add_f32_e32 v241, v95, v241
	v_exp_f32_e32 v69, v69
	v_add_f32_e32 v241, v96, v241
	v_exp_f32_e32 v70, v70
	v_add_f32_e32 v241, v97, v241
	v_exp_f32_e32 v71, v71
	v_add_f32_e32 v241, v98, v241
	v_exp_f32_e32 v72, v72
	v_add_f32_e32 v241, v68, v241
	v_exp_f32_e32 v73, v73
	v_add_f32_e32 v241, v69, v241
	v_exp_f32_e32 v74, v74
	v_add_f32_e32 v241, v70, v241
	v_add_f32_e32 v241, v71, v241
	v_exp_f32_e32 v75, v76
	v_add_f32_e32 v241, v72, v241
	v_exp_f32_e32 v76, v77
	v_add_f32_e32 v241, v73, v241
	v_exp_f32_e32 v77, v78
	v_add_f32_e32 v241, v74, v241
	v_exp_f32_e32 v78, v79
	v_add_f32_e32 v241, v84, v241
	v_exp_f32_e32 v79, v80
	v_add_f32_e32 v241, v75, v241
	v_exp_f32_e32 v80, v81
	v_add_f32_e32 v241, v76, v241
	v_exp_f32_e32 v81, v82
	v_add_f32_e32 v241, v77, v241
	v_exp_f32_e32 v82, v83
	v_add_f32_e32 v241, v78, v241
	v_add_f32_e32 v241, v79, v241
	v_add_f32_e32 v241, v80, v241
	v_add_f32_e32 v241, v81, v241
	v_add_f32_e32 v241, v82, v241
	v_mov_b32_e32 v99, v241
	s_nop 1
	v_permlane32_swap_b32_e32 v241, v99
	v_cmp_gt_f32_e32 vcc, 1.0, v165
	s_cbranch_vccz .LBB0_954
	s_and_saveexec_b64 s[12:13], s[10:11]
	ds_write_b32 v155, v165 offset:128
	s_or_b64 exec, exec, s[12:13]
	s_waitcnt lgkmcnt(0)
	v_add_u32_e32 v180, s78, v2
	ds_read_b128 v[168:171], v180 offset:224
	ds_read_b128 v[172:175], v180 offset:192
	ds_read_b128 v[176:179], v180 offset:160
	ds_read_b128 v[180:183], v180 offset:128
	s_waitcnt lgkmcnt(0)
	s_waitcnt lgkmcnt(0)
	v_pk_mul_f32 v[64:65], v[168:169], v[64:65]
	v_pk_mul_f32 v[60:61], v[172:173], v[60:61]
	v_pk_mul_f32 v[56:57], v[176:177], v[56:57]
	v_pk_mul_f32 v[66:67], v[170:171], v[66:67]
	v_pk_mul_f32 v[62:63], v[174:175], v[62:63]
	v_pk_mul_f32 v[58:59], v[178:179], v[58:59]
	v_pk_mul_f32 v[54:55], v[182:183], v[54:55]
	v_pk_mul_f32 v[52:53], v[180:181], v[52:53]
	v_pk_mul_f32 v[48:49], v[168:169], v[48:49]
	v_pk_mul_f32 v[44:45], v[172:173], v[44:45]
	v_pk_mul_f32 v[40:41], v[176:177], v[40:41]
	v_pk_mul_f32 v[50:51], v[170:171], v[50:51]
	v_pk_mul_f32 v[46:47], v[174:175], v[46:47]
	v_pk_mul_f32 v[42:43], v[178:179], v[42:43]
	v_pk_mul_f32 v[38:39], v[182:183], v[38:39]
	v_pk_mul_f32 v[36:37], v[180:181], v[36:37]
	v_pk_mul_f32 v[32:33], v[168:169], v[32:33]
	v_pk_mul_f32 v[28:29], v[172:173], v[28:29]
	v_pk_mul_f32 v[24:25], v[176:177], v[24:25]
	v_pk_mul_f32 v[34:35], v[170:171], v[34:35]
	v_pk_mul_f32 v[30:31], v[174:175], v[30:31]
	v_pk_mul_f32 v[26:27], v[178:179], v[26:27]
	v_pk_mul_f32 v[22:23], v[182:183], v[22:23]
	v_pk_mul_f32 v[20:21], v[180:181], v[20:21]
	v_pk_mul_f32 v[16:17], v[168:169], v[16:17]
	v_pk_mul_f32 v[12:13], v[172:173], v[12:13]
	v_pk_mul_f32 v[8:9], v[176:177], v[8:9]
	v_pk_mul_f32 v[18:19], v[170:171], v[18:19]
	v_pk_mul_f32 v[14:15], v[174:175], v[14:15]
	v_pk_mul_f32 v[10:11], v[178:179], v[10:11]
	v_pk_mul_f32 v[6:7], v[182:183], v[6:7]
	v_pk_mul_f32 v[4:5], v[180:181], v[4:5]
.LBB0_954:
	v_cvt_pk_bf16_f32 v168, v166, v85
	v_cvt_pk_bf16_f32 v169, v86, v87
	v_cvt_pk_bf16_f32 v170, v88, v89
	v_cvt_pk_bf16_f32 v171, v90, v167
	v_cvt_pk_bf16_f32 v86, v91, v92
	v_cvt_pk_bf16_f32 v87, v93, v94
	v_cvt_pk_bf16_f32 v88, v95, v96
	v_cvt_pk_bf16_f32 v89, v97, v98
	v_cvt_pk_bf16_f32 v68, v68, v69
	v_cvt_pk_bf16_f32 v69, v70, v71
	v_cvt_pk_bf16_f32 v70, v72, v73
	v_cvt_pk_bf16_f32 v71, v74, v84
	v_cvt_pk_bf16_f32 v72, v75, v76
	v_cvt_pk_bf16_f32 v73, v77, v78
	v_cvt_pk_bf16_f32 v74, v79, v80
	v_cvt_pk_bf16_f32 v75, v81, v82
	s_waitcnt lgkmcnt(0)
	v_add_f32_e32 v99, v241, v99
	v_fma_f32 v163, v163, v165, v99
	v_mfma_f32_32x32x16_bf16 v[52:67], v[168:171], v[144:147], v[52:67]
	v_mfma_f32_32x32x16_bf16 v[52:67], v[86:89], v[140:143], v[52:67]
	v_mfma_f32_32x32x16_bf16 v[52:67], v[68:71], v[136:139], v[52:67]
	v_mfma_f32_32x32x16_bf16 v[52:67], v[72:75], v[132:135], v[52:67]
	ds_read_b64_tr_b16 v[76:77], v164 offset:0x400
	ds_read_b64_tr_b16 v[78:79], v164 offset:0xc00
	ds_read_b64_tr_b16 v[80:81], v164 offset:0x1400
	ds_read_b64_tr_b16 v[82:83], v164 offset:0x1c00
	ds_read_b64_tr_b16 v[90:91], v164 offset:0x2400
	ds_read_b64_tr_b16 v[92:93], v164 offset:0x2c00
	ds_read_b64_tr_b16 v[94:95], v164 offset:0x3400
	ds_read_b64_tr_b16 v[96:97], v164 offset:0x3c00
	v_mfma_f32_32x32x16_bf16 v[36:51], v[168:171], v[128:131], v[36:51]
	v_mfma_f32_32x32x16_bf16 v[36:51], v[86:89], v[124:127], v[36:51]
	v_mfma_f32_32x32x16_bf16 v[36:51], v[68:71], v[120:123], v[36:51]
	v_mfma_f32_32x32x16_bf16 v[36:51], v[72:75], v[116:119], v[36:51]
	ds_read_b64_tr_b16 v[116:117], v164 offset:0x600
	ds_read_b64_tr_b16 v[118:119], v164 offset:0xe00
	ds_read_b64_tr_b16 v[120:121], v164 offset:0x1600
	ds_read_b64_tr_b16 v[122:123], v164 offset:0x1e00
	ds_read_b64_tr_b16 v[124:125], v164 offset:0x2600
	ds_read_b64_tr_b16 v[126:127], v164 offset:0x2e00
	ds_read_b64_tr_b16 v[128:129], v164 offset:0x3600
	ds_read_b64_tr_b16 v[130:131], v164 offset:0x3e00
	s_waitcnt lgkmcnt(8)
	v_mfma_f32_32x32x16_bf16 v[20:35], v[168:171], v[76:79], v[20:35]
	v_mfma_f32_32x32x16_bf16 v[20:35], v[86:89], v[80:83], v[20:35]
	v_mfma_f32_32x32x16_bf16 v[20:35], v[68:71], v[90:93], v[20:35]
	v_mfma_f32_32x32x16_bf16 v[20:35], v[72:75], v[94:97], v[20:35]
	s_waitcnt lgkmcnt(0)
	v_mfma_f32_32x32x16_bf16 v[4:19], v[168:171], v[116:119], v[4:19]
	v_mfma_f32_32x32x16_bf16 v[4:19], v[86:89], v[120:123], v[4:19]
	v_mfma_f32_32x32x16_bf16 v[4:19], v[68:71], v[124:127], v[4:19]
	v_mfma_f32_32x32x16_bf16 v[4:19], v[72:75], v[128:131], v[4:19]
	s_add_i32 s3, s2, 0x80
	s_cmp_gt_i32 s3, s80
	s_cbranch_scc1 .LBB0_942

.LBB0_958:
	v_exp_f32_e32 v166, v84
	v_exp_f32_e32 v85, v85
	v_exp_f32_e32 v86, v86
	v_exp_f32_e32 v87, v87
	v_exp_f32_e32 v88, v88
	v_exp_f32_e32 v89, v89
	v_exp_f32_e32 v90, v90
	v_exp_f32_e32 v167, v91
	v_exp_f32_e32 v84, v75
	v_exp_f32_e32 v91, v92
	v_exp_f32_e32 v92, v93
	v_exp_f32_e32 v93, v94
	v_exp_f32_e32 v94, v95
	v_exp_f32_e32 v95, v96
	v_exp_f32_e32 v96, v97
	v_exp_f32_e32 v97, v98
	v_exp_f32_e32 v98, v99
	v_add_f32_e32 v241, v85, v166
	v_add_f32_e32 v241, v86, v241
	v_add_f32_e32 v241, v87, v241
	v_add_f32_e32 v241, v88, v241
	v_add_f32_e32 v241, v89, v241
	v_add_f32_e32 v241, v90, v241
	v_add_f32_e32 v241, v167, v241
	v_add_f32_e32 v241, v91, v241
	v_add_f32_e32 v241, v92, v241
	v_add_f32_e32 v241, v93, v241
	v_add_f32_e32 v241, v94, v241
	v_exp_f32_e32 v68, v68
	v_add_f32_e32 v241, v95, v241
	v_exp_f32_e32 v69, v69
	v_add_f32_e32 v241, v96, v241
	v_exp_f32_e32 v70, v70
	v_add_f32_e32 v241, v97, v241
	v_exp_f32_e32 v71, v71
	v_add_f32_e32 v241, v98, v241
	v_exp_f32_e32 v72, v72
	v_add_f32_e32 v241, v68, v241
	v_exp_f32_e32 v73, v73
	v_add_f32_e32 v241, v69, v241
	v_exp_f32_e32 v74, v74
	v_add_f32_e32 v241, v70, v241
	v_add_f32_e32 v241, v71, v241
	v_exp_f32_e32 v75, v76
	v_add_f32_e32 v241, v72, v241
	v_exp_f32_e32 v76, v77
	v_add_f32_e32 v241, v73, v241
	v_exp_f32_e32 v77, v78
	v_add_f32_e32 v241, v74, v241
	v_exp_f32_e32 v78, v79
	v_add_f32_e32 v241, v84, v241
	v_exp_f32_e32 v79, v80
	v_add_f32_e32 v241, v75, v241
	v_exp_f32_e32 v80, v81
	v_add_f32_e32 v241, v76, v241
	v_exp_f32_e32 v81, v82
	v_add_f32_e32 v241, v77, v241
	v_exp_f32_e32 v82, v83
	v_add_f32_e32 v241, v78, v241
	v_add_f32_e32 v241, v79, v241
	v_add_f32_e32 v241, v80, v241
	v_add_f32_e32 v241, v81, v241
	v_add_f32_e32 v241, v82, v241
	v_mov_b32_e32 v99, v241
	s_nop 1
	v_permlane32_swap_b32_e32 v241, v99
	v_cmp_gt_f32_e32 vcc, 1.0, v165
	s_cbranch_vccz .LBB0_941
	s_and_saveexec_b64 s[12:13], s[10:11]
	s_cbranch_execz .LBB0_940
	ds_write_b32 v155, v165 offset:128
	s_branch .LBB0_940
.LBB0_961:
	v_sub_f32_e32 v241, v166, v184
	v_max_f32_e32 v241, v162, v241
	v_sub_f32_e32 v165, v162, v241
	v_exp_f32_e32 v165, v165
	v_add_f32_e32 v242, v241, v184
	v_mov_b32_e32 v162, v241
	v_sub_f32_e32 v84, v84, v242
	v_sub_f32_e32 v85, v85, v242
	v_sub_f32_e32 v86, v86, v242
	v_sub_f32_e32 v87, v87, v242
	v_sub_f32_e32 v88, v88, v242
	v_sub_f32_e32 v89, v89, v242
	v_sub_f32_e32 v90, v90, v242
	v_sub_f32_e32 v91, v91, v242
	v_sub_f32_e32 v92, v92, v242
	v_sub_f32_e32 v93, v93, v242
	v_sub_f32_e32 v94, v94, v242
	v_sub_f32_e32 v95, v95, v242
	v_sub_f32_e32 v96, v96, v242
	v_sub_f32_e32 v97, v97, v242
	v_sub_f32_e32 v98, v98, v242
	v_sub_f32_e32 v99, v99, v242
	v_sub_f32_e32 v68, v68, v242
	v_sub_f32_e32 v69, v69, v242
	v_sub_f32_e32 v70, v70, v242
	v_sub_f32_e32 v71, v71, v242
	v_sub_f32_e32 v72, v72, v242
	v_sub_f32_e32 v73, v73, v242
	v_sub_f32_e32 v74, v74, v242
	v_sub_f32_e32 v75, v75, v242
	v_sub_f32_e32 v76, v76, v242
	v_sub_f32_e32 v77, v77, v242
	v_sub_f32_e32 v78, v78, v242
	v_sub_f32_e32 v79, v79, v242
	v_sub_f32_e32 v80, v80, v242
	v_sub_f32_e32 v81, v81, v242
	v_sub_f32_e32 v82, v82, v242
	v_sub_f32_e32 v83, v83, v242
	v_cmp_lt_f32_e32 vcc, 0xf0000000, v241
	v_sub_f32_e32 v242, 0, v241
	s_nop 0
	v_cndmask_b32_e32 v242, 0, v242, vcc
	v_add_f32_e32 v240, v241, v242
	v_add_f32_e32 v239, s91, v240
	v_mov_b32_e32 v184, v242
	v_mov_b32_e32 v185, v242
	v_mov_b32_e32 v186, v242
	v_mov_b32_e32 v187, v242
	v_mov_b32_e32 v188, v242
	v_mov_b32_e32 v189, v242
	v_mov_b32_e32 v190, v242
	v_mov_b32_e32 v191, v242
	v_mov_b32_e32 v192, v242
	v_mov_b32_e32 v193, v242
	v_mov_b32_e32 v194, v242
	v_mov_b32_e32 v195, v242
	v_mov_b32_e32 v196, v242
	v_mov_b32_e32 v197, v242
	v_mov_b32_e32 v198, v242
	v_mov_b32_e32 v199, v242
	s_branch .LBB0_950
.LBB0_962:
	v_sub_f32_e32 v241, v166, v184
	v_max_f32_e32 v241, v162, v241
	v_sub_f32_e32 v165, v162, v241
	v_exp_f32_e32 v165, v165
	v_add_f32_e32 v242, v241, v184
	v_mov_b32_e32 v162, v241
	v_sub_f32_e32 v84, v84, v242
	v_sub_f32_e32 v85, v85, v242
	v_sub_f32_e32 v86, v86, v242
	v_sub_f32_e32 v87, v87, v242
	v_sub_f32_e32 v88, v88, v242
	v_sub_f32_e32 v89, v89, v242
	v_sub_f32_e32 v90, v90, v242
	v_sub_f32_e32 v91, v91, v242
	v_sub_f32_e32 v92, v92, v242
	v_sub_f32_e32 v93, v93, v242
	v_sub_f32_e32 v94, v94, v242
	v_sub_f32_e32 v95, v95, v242
	v_sub_f32_e32 v96, v96, v242
	v_sub_f32_e32 v97, v97, v242
	v_sub_f32_e32 v98, v98, v242
	v_sub_f32_e32 v99, v99, v242
	v_sub_f32_e32 v68, v68, v242
	v_sub_f32_e32 v69, v69, v242
	v_sub_f32_e32 v70, v70, v242
	v_sub_f32_e32 v71, v71, v242
	v_sub_f32_e32 v72, v72, v242
	v_sub_f32_e32 v73, v73, v242
	v_sub_f32_e32 v74, v74, v242
	v_sub_f32_e32 v75, v75, v242
	v_sub_f32_e32 v76, v76, v242
	v_sub_f32_e32 v77, v77, v242
	v_sub_f32_e32 v78, v78, v242
	v_sub_f32_e32 v79, v79, v242
	v_sub_f32_e32 v80, v80, v242
	v_sub_f32_e32 v81, v81, v242
	v_sub_f32_e32 v82, v82, v242
	v_sub_f32_e32 v83, v83, v242
	v_cmp_lt_f32_e32 vcc, 0xf0000000, v241
	v_sub_f32_e32 v242, 0, v241
	s_nop 0
	v_cndmask_b32_e32 v242, 0, v242, vcc
	v_add_f32_e32 v240, v241, v242
	v_add_f32_e32 v239, s91, v240
	v_mov_b32_e32 v184, v242
	v_mov_b32_e32 v185, v242
	v_mov_b32_e32 v186, v242
	v_mov_b32_e32 v187, v242
	v_mov_b32_e32 v188, v242
	v_mov_b32_e32 v189, v242
	v_mov_b32_e32 v190, v242
	v_mov_b32_e32 v191, v242
	v_mov_b32_e32 v192, v242
	v_mov_b32_e32 v193, v242
	v_mov_b32_e32 v194, v242
	v_mov_b32_e32 v195, v242
	v_mov_b32_e32 v196, v242
	v_mov_b32_e32 v197, v242
	v_mov_b32_e32 v198, v242
	v_mov_b32_e32 v199, v242
	s_branch .LBB0_958
	s_nop 0
	s_nop 0
	s_nop 0
	s_nop 0
	s_nop 0
	s_nop 0
	s_nop 0
	s_nop 0
	s_nop 0
	s_nop 0
	s_nop 0
	s_nop 0
	s_nop 0
	s_nop 0
